# PEER table conversion in scan phase: split 24/8 between context and latent workgroups, coalesced double-buffered loads with hardware fp4 convert and LDS regroup
# speedup vs baseline: 1.1311x; 1.0104x over previous
.LBB0_226:
	v_readlane_b32 s4, v253, 0
	s_and_b32 s33, s4, 7
	s_mov_b64 s[6:7], s[80:81]
	s_xor_b32 s2, s33, 7
	s_add_i32 s2, s6, s2
	s_lshr_b32 s83, s2, 3
	s_cmpk_lt_u32 s4, 0xf00
	s_cselect_b64 s[2:3], -1, 0
	v_readlane_b32 s5, v253, 1
	v_writelane_b32 v253, s2, 22
	s_mul_i32 s1, s7, s6
	s_mul_i32 s97, s1, s0
	v_writelane_b32 v253, s3, 23
	s_lshr_b32 s2, s4, 3
	v_writelane_b32 v253, s2, 24
	s_lshl_b32 s2, s33, 7
	s_add_u32 s0, s68, 0x38e00200
	v_writelane_b32 v253, s2, 25
	s_addc_u32 s1, s69, 0
	v_writelane_b32 v253, s0, 26
	v_lshrrev_b32_e32 v1, 20, v0
	v_lshrrev_b32_e32 v0, 10, v0
	v_writelane_b32 v253, s1, 27
	s_add_u32 s0, s68, 0x38e00400
	s_addc_u32 s1, s69, 0
	v_writelane_b32 v253, s0, 18
	v_or_b32_e32 v0, v0, v1
	s_mov_b32 s81, 0
	v_writelane_b32 v253, s1, 19
	s_add_u32 s0, s68, 0x38e00500
	s_addc_u32 s1, s69, 0
	v_writelane_b32 v253, s0, 10
	s_mov_b32 s7, s81
	s_mov_b32 s30, 2
	v_writelane_b32 v253, s1, 11
	s_add_u32 s0, s68, 0x38e00600
	s_addc_u32 s1, s69, 0
	v_writelane_b32 v253, s0, 12
	s_movk_i32 s89, 0xff00
	s_movk_i32 s91, 0xff
	v_writelane_b32 v253, s1, 13
	s_add_u32 s0, s68, 0x38e00700
	s_addc_u32 s1, s69, 0
	v_writelane_b32 v253, s0, 14
	v_mov_b32_e32 v129, 0
	s_mov_b64 s[40:41], 0
	v_writelane_b32 v253, s1, 15
	s_add_u32 s0, s68, 0x38e00800
	s_addc_u32 s1, s69, 0
	v_writelane_b32 v253, s0, 16
	s_mov_b64 s[86:87], 0x1a00080
	s_mov_b64 s[36:37], 0xa3ff000
	v_writelane_b32 v253, s1, 17
	s_add_u32 s0, s68, 0x38e00900
	s_addc_u32 s1, s69, 0
	v_writelane_b32 v253, s0, 28
	v_mov_b32_e32 v178, 0x12004
	v_mov_b32_e32 v179, 1
	v_writelane_b32 v253, s1, 29
	s_add_u32 s0, s68, 0x38e00a00
	s_addc_u32 s1, s69, 0
	v_writelane_b32 v253, s0, 30
	s_mov_b32 s88, 0x3e38aa3b
	s_movk_i32 s10, 0x1f8
	v_writelane_b32 v253, s1, 31
	s_add_u32 s0, s68, 0x38e00b00
	s_addc_u32 s1, s69, 0
	v_writelane_b32 v253, s0, 32
	s_brev_b32 s11, -2
	s_brev_b32 s12, 18
	v_writelane_b32 v253, s1, 33
	s_add_u32 s0, s68, 0x38e00c00
	s_addc_u32 s1, s69, 0
	v_writelane_b32 v253, s0, 34
	s_mov_b32 s13, 0x800000
	s_brev_b32 s14, 1
	v_writelane_b32 v253, s1, 35
	s_add_u32 s0, s68, 0x38e00d00
	s_addc_u32 s1, s69, 0
	v_writelane_b32 v253, s0, 36
	v_mov_b32_e32 v180, 0x3c0881c4
	v_mov_b32_e32 v181, 0xbab64f3b
	v_writelane_b32 v253, s1, 37
	s_add_u32 s0, s68, 0x38e00e00
	s_addc_u32 s1, s69, 0
	v_writelane_b32 v253, s0, 38
	s_mov_b32 s15, 0x3e800000
	s_mov_b32 s16, 0x3f400000
	v_writelane_b32 v253, s1, 39
	s_add_u32 s0, s68, 0x38e00f00
	s_addc_u32 s1, s69, 0
	v_writelane_b32 v253, s0, 40
	s_mov_b32 s17, 0x3fa00000
	s_mov_b32 s18, 0x3fe00000
	v_writelane_b32 v253, s1, 41
	s_add_u32 s0, s68, 0x38e01000
	s_addc_u32 s1, s69, 0
	v_writelane_b32 v253, s0, 42
	s_mov_b32 s19, 0x40200000
	s_mov_b32 s20, 0x40600000
	v_writelane_b32 v253, s1, 43
	s_add_u32 s0, s68, 0x38e01100
	s_addc_u32 s1, s69, 0
	v_writelane_b32 v253, s0, 44
	s_mov_b32 s21, 0x40a00000
	s_movk_i32 s22, 0x1fff
	v_writelane_b32 v253, s1, 45
	s_add_u32 s0, s68, 0x38e01200
	s_addc_u32 s1, s69, 0
	v_writelane_b32 v253, s0, 46
	s_movk_i32 s23, 0x6000
	s_mov_b32 s24, 0xa000
	v_writelane_b32 v253, s1, 47
	s_add_u32 s0, s68, 0x38e01300
	s_addc_u32 s1, s69, 0
	v_writelane_b32 v253, s0, 48
	s_cmp_eq_u32 s63, 15
	s_mov_b32 s25, 0x13600000
	v_writelane_b32 v253, s1, 49
	s_cselect_b64 s[0:1], -1, 0
	v_writelane_b32 v253, s0, 50
	s_cmp_eq_u32 s63, 14
	s_mov_b32 s26, 0x9fff
	v_writelane_b32 v253, s1, 51
	s_cselect_b64 s[0:1], -1, 0
	v_writelane_b32 v253, s0, 52
	s_cmp_eq_u32 s63, 13
	v_mov_b32_e32 v182, 0x3727c5ac
	v_writelane_b32 v253, s1, 53
	s_cselect_b64 s[0:1], -1, 0
	v_writelane_b32 v253, s0, 54
	s_cmp_eq_u32 s63, 12
	s_movk_i32 s28, 0x7f
	v_writelane_b32 v253, s1, 55
	s_cselect_b64 s[0:1], -1, 0
	v_writelane_b32 v253, s0, 56
	s_cmp_eq_u32 s63, 11
	s_movk_i32 s29, 0x7f00
	v_writelane_b32 v253, s1, 57
	s_cselect_b64 s[0:1], -1, 0
	v_writelane_b32 v253, s0, 58
	s_cmp_eq_u32 s63, 10
	v_mov_b32_e32 v183, 0x7f
	v_writelane_b32 v253, s1, 59
	s_cselect_b64 s[0:1], -1, 0
	v_writelane_b32 v253, s0, 60
	s_cmp_eq_u32 s63, 9
	v_mov_b32_e32 v184, 0x7d
	v_writelane_b32 v253, s1, 61
	s_cselect_b64 s[0:1], -1, 0
	v_writelane_b32 v253, s0, 62
	s_cmp_eq_u32 s63, 8
	s_mov_b32 s82, 0x41d00000
	v_writelane_b32 v253, s1, 63
	s_cselect_b64 s[0:1], -1, 0
	v_writelane_b32 v254, s0, 0
	s_cmp_eq_u32 s63, 7
	v_mov_b32_e32 v185, 0x7b
	v_writelane_b32 v254, s1, 1
	s_cselect_b64 s[0:1], -1, 0
	v_writelane_b32 v254, s0, 2
	s_cmp_eq_u32 s63, 6
	v_mov_b32_e32 v186, 0x79
	v_writelane_b32 v254, s1, 3
	s_cselect_b64 s[0:1], -1, 0
	v_writelane_b32 v254, s0, 4
	s_cmp_eq_u32 s63, 5
	s_mov_b32 s90, 0x3d1d89d9
	v_writelane_b32 v254, s1, 5
	s_cselect_b64 s[0:1], -1, 0
	v_writelane_b32 v254, s0, 6
	s_cmp_eq_u32 s63, 4
	v_not_b32_e32 v187, 63
	v_writelane_b32 v254, s1, 7
	s_cselect_b64 s[0:1], -1, 0
	v_writelane_b32 v254, s0, 8
	s_cmp_eq_u32 s63, 3
	v_mov_b32_e32 v189, 0xf149f2ca
	v_writelane_b32 v254, s1, 9
	s_cselect_b64 s[0:1], -1, 0
	v_writelane_b32 v254, s0, 10
	s_cmp_eq_u32 s63, 2
	v_not_b32_e32 v190, 31
	v_writelane_b32 v254, s1, 11
	s_cselect_b64 s[0:1], -1, 0
	v_writelane_b32 v254, s0, 12
	s_cmp_eq_u32 s63, 1
	v_mov_b32_e32 v191, 0x7fc00000
	v_writelane_b32 v254, s1, 13
	s_cselect_b64 s[0:1], -1, 0
	v_writelane_b32 v254, s0, 14
	s_cmp_eq_u32 s63, 0
	s_nop 0
	v_writelane_b32 v254, s1, 15
	s_cselect_b64 s[0:1], -1, 0
	v_writelane_b32 v254, s0, 16
	s_nop 1
	v_writelane_b32 v254, s1, 17
	s_lshl_b32 s0, s63, 8
	s_add_u32 s0, s76, s0
	s_addc_u32 s1, s77, 0
	s_add_u32 s2, s0, 0x1400
	s_addc_u32 s3, s1, 0
	v_writelane_b32 v254, s2, 18
	s_add_u32 s0, s0, 0x2400
	s_addc_u32 s1, s1, 0
	v_writelane_b32 v254, s3, 19
	v_writelane_b32 v254, s0, 20
	s_nop 1
	v_writelane_b32 v254, s1, 21
	s_add_u32 s0, s68, 0x38e03400
	s_addc_u32 s1, s69, 0
	v_writelane_b32 v254, s0, 22
	s_nop 1
	v_writelane_b32 v254, s1, 23
	s_add_u32 s0, s68, 0x38e03500
	s_addc_u32 s1, s69, 0
	v_writelane_b32 v254, s0, 24
	s_cmpk_lt_i32 s4, 0x1400
	s_mov_b64 s[68:69], 0xb3fec00
	v_writelane_b32 v254, s1, 25
	s_movk_i32 s0, 0x3ff
	v_and_or_b32 v0, v0, s0, v133
	v_cmp_eq_u32_e64 s[0:1], 0, v0
	v_mov_b32_e32 v0, 0x100
	v_sub_co_u32_e32 v0, vcc, s4, v0
	v_writelane_b32 v254, s0, 26
	s_nop 1
	v_writelane_b32 v254, s1, 27
	s_cselect_b64 s[0:1], -1, 0
	v_writelane_b32 v254, s0, 28
	s_cmpk_lt_u32 s4, 0xa00
	s_nop 0
	v_writelane_b32 v254, s1, 29
	s_cselect_b64 s[0:1], -1, 0
	v_writelane_b32 v254, s0, 30
	s_add_i32 s2, s6, 0xffffff00
	s_nop 0
	v_writelane_b32 v254, s1, 31
	s_and_b64 s[0:1], vcc, exec
	v_writelane_b32 v254, s2, 32
	s_cselect_b32 s0, 0x100000, s2
	s_cmpk_gt_u32 s6, 0x13f
	v_readfirstlane_b32 s1, v0
	s_cselect_b32 s0, s0, s6
	s_add_i32 s98, s4, 0x1800
	s_cmpk_lt_u32 s4, 0x100
	s_cselect_b32 s98, s98, s1
	s_cmpk_eq_u32 s6, 0x200
	s_cselect_b32 s1, s98, s1
	s_cselect_b64 s[98:99], -1, 0
	s_cmpk_lt_i32 s4, 0x500
	v_writelane_b32 v254, s1, 33
	v_writelane_b32 v254, s0, 34
	s_cselect_b64 s[0:1], -1, 0
	v_writelane_b32 v254, s0, 35
	s_cmpk_gt_u32 s6, 0x1ff
	s_nop 0
	v_writelane_b32 v254, s1, 36
	s_cselect_b64 s[0:1], -1, 0
	s_cmpk_gt_u32 s4, 0xff
	s_cselect_b64 s[2:3], -1, 0
	s_and_b64 s[0:1], s[2:3], s[0:1]
	s_cmpk_lt_i32 s4, 0x2100
	s_cselect_b64 s[2:3], -1, 0
	s_and_b64 s[0:1], s[2:3], s[0:1]
	s_lshl_b64 s[76:77], s[6:7], 8
	s_or_b64 s[0:1], s[0:1], s[98:99]
	v_writelane_b32 v254, s0, 37
	s_cmpk_lt_u32 s4, 0x1400
	v_readlane_b32 s2, v253, 20
	v_writelane_b32 v254, s1, 38
	s_cselect_b64 s[0:1], -1, 0
	v_writelane_b32 v254, s0, 39
	s_lshl_b32 s84, s6, 2
	v_readlane_b32 s3, v253, 21
	v_writelane_b32 v254, s1, 40
	s_bfe_i32 s0, s6, 0x1001d
	v_writelane_b32 v254, s0, 41
	s_abs_i32 s0, s84
	v_cvt_f32_u32_e32 v0, s0
	v_writelane_b32 v254, s0, 42
	s_sub_i32 s0, 0, s0
	s_lshl_b64 s[8:9], s[2:3], 4
	v_rcp_iflag_f32_e32 v0, v0
	s_lshl_b32 s1, s33, 18
	s_lshl_b32 s5, s4, 2
	s_mov_b64 s[34:35], s[76:77]
	v_mul_f32_e32 v0, 0x4f7ffffe, v0
	v_cvt_u32_f32_e32 v0, v0
	v_mul_lo_u32 v1, s0, v0
	v_readlane_b32 s0, v254, 33
	s_lshl_b32 s0, s0, 13
	v_writelane_b32 v254, s0, 43
	s_lshl_b32 s0, s6, 13
	s_add_i32 s0, s0, 0xffe00000
	v_writelane_b32 v254, s0, 44
	v_writelane_b32 v254, s8, 45
	s_mov_b32 s0, s6
	v_mul_hi_u32 v1, v0, v1
	v_writelane_b32 v254, s9, 46
	s_lshl_b64 s[8:9], s[6:7], 13
	v_writelane_b32 v254, s8, 47
	s_lshl_b64 s[6:7], s[6:7], 12
	s_add_u32 s2, s2, s76
	v_writelane_b32 v254, s9, 48
	v_writelane_b32 v254, s0, 49
	s_addc_u32 s3, s3, s77
	s_ashr_i32 s85, s84, 31
	v_writelane_b32 v254, s1, 50
	v_writelane_b32 v254, s6, 51
	v_add_u32_e32 v176, v0, v1
	s_add_i32 s0, s84, s5
	v_writelane_b32 v254, s7, 52
	v_writelane_b32 v254, s2, 53
	s_lshl_b64 s[6:7], s[84:85], 12
	v_writelane_b32 v253, s6, 8
	v_writelane_b32 v254, s3, 54
	v_writelane_b32 v254, s5, 55
	v_writelane_b32 v254, s0, 56
	s_lshl_b32 s2, s33, 17
	v_mbcnt_lo_u32_b32 v0, -1, 0
	s_lshl_b64 s[4:5], s[84:85], 11
	v_writelane_b32 v253, s7, 9
	s_movk_i32 s85, 0x90
	s_movk_i32 s6, 0x4400
	s_movk_i32 s7, 0x110
	s_movk_i32 s8, 0xf7
	s_movk_i32 s9, 0x101
	s_mov_b32 s0, 0x3fd744fd
	s_lshl_b32 s27, s2, 1
	v_mbcnt_hi_u32_b32 v188, -1, v0
	v_writelane_b32 v254, s97, 57
	s_branch .LBB0_230

.LBB0_633:
	v_readlane_b32 s2, v254, 37
	v_readlane_b32 s3, v254, 38
	v_readlane_b32 s60, v255, 0
	s_and_b64 vcc, exec, s[2:3]
	v_readlane_b32 s97, v254, 57
	s_mov_b64 s[76:77], s[34:35]
	v_readlane_b32 s61, v255, 1
	s_cbranch_vccz .LBB0_641
	v_readlane_b32 s98, v253, 0
	v_readlane_b32 s99, v254, 32
	s_cmpk_eq_u32 s99, 0x100
	s_movk_i32 s99, 0x2000
	s_cselect_b32 s99, 0x1800, s99
	s_cmpk_lt_u32 s98, 0x100
	s_cselect_b32 s98, 0x2000, s99
	v_readlane_b32 s2, v254, 60
	v_readlane_b32 s3, v254, 61
	s_lshl_b32 s2, s2, 25
	v_readlane_b32 s3, v254, 43
	v_readlane_b32 s38, v254, 33
	s_waitcnt lgkmcnt(0)
	v_readlane_b32 s99, v254, 32
	v_readlane_b32 s100, v254, 44
	v_and_b32_e32 v0, 63, v133
	v_lshrrev_b32_e32 v1, 6, v133
	v_mul_u32_u24_e32 v2, 0x4200, v1
	v_lshl_add_u32 v200, v0, 1, v2
	v_lshl_add_u32 v201, v0, 4, v2
	v_lshlrev_b32_e32 v3, 13, v1
	v_lshl_add_u32 v202, v0, 4, v3
	v_mov_b32_e32 v203, 0
	v_lshrrev_b32_e32 v4, 3, v133
	v_and_b32_e32 v4, 3, v4
	v_lshlrev_b32_e32 v4, 21, v4
	v_lshrrev_b32_e32 v5, 5, v133
	v_lshl_add_u32 v4, v5, 7, v4
	v_and_b32_e32 v5, 7, v133
	v_lshl_add_u32 v204, v5, 4, v4
	v_mov_b32_e32 v205, 0
	s_cmpk_gt_i32 s38, 0xfff
	s_cselect_b32 s42, s54, s52
	s_cselect_b32 s43, s55, s53
	s_mov_b32 s46, 0x2c00000
	s_cselect_b32 s46, 0xac00000, s46
	s_mov_b32 s44, 0x42800000
	s_cselect_b32 s44, 0x41500000, s44
	s_and_b32 s39, s3, 0x1ffe000
	s_or_b32 s80, s39, s2
	s_lshl_b32 s39, s80, 2
	s_add_u32 s42, s42, s39
	s_addc_u32 s43, s43, 0
	v_lshl_add_u64 v[0:1], s[42:43], 0, v[202:203]
	s_add_u32 s42, s42, 0x1000
	s_addc_u32 s43, s43, 0
	v_lshl_add_u64 v[2:3], s[42:43], 0, v[202:203]
	global_load_dwordx4 v[142:145], v[0:1], off
	global_load_dwordx4 v[146:149], v[0:1], off offset:1024
	global_load_dwordx4 v[150:153], v[0:1], off offset:2048
	global_load_dwordx4 v[154:157], v[0:1], off offset:3072
	global_load_dwordx4 v[158:161], v[2:3], off
	global_load_dwordx4 v[162:165], v[2:3], off offset:1024
	global_load_dwordx4 v[166:169], v[2:3], off offset:2048
	global_load_dwordx4 v[170:173], v[2:3], off offset:3072
	s_lshr_b32 s39, s80, 1
	s_and_b32 s39, s39, 0x3800000
	s_lshr_b32 s47, s80, 3
	s_and_b32 s47, s47, 0x1fff80
	s_or_b32 s39, s39, s47
	s_add_u32 s46, s46, s39
	s_add_u32 s46, s58, s46
	s_addc_u32 s47, s59, 0
	v_lshl_add_u64 v[240:241], s[46:47], 0, v[204:205]
	v_mov_b32_e32 v8, s44
.Lcv_loop:
	s_add_i32 s38, s38, s99
	s_add_i32 s3, s3, s100
	s_cmp_lt_i32 s38, s98
	s_cbranch_scc0 .Lcv_lastA
	s_cmpk_gt_i32 s38, 0xfff
	s_cselect_b32 s42, s54, s52
	s_cselect_b32 s43, s55, s53
	s_mov_b32 s46, 0x2c00000
	s_cselect_b32 s46, 0xac00000, s46
	s_mov_b32 s44, 0x42800000
	s_cselect_b32 s44, 0x41500000, s44
	s_and_b32 s39, s3, 0x1ffe000
	s_or_b32 s80, s39, s2
	s_lshl_b32 s39, s80, 2
	s_add_u32 s42, s42, s39
	s_addc_u32 s43, s43, 0
	v_lshl_add_u64 v[0:1], s[42:43], 0, v[202:203]
	s_add_u32 s42, s42, 0x1000
	s_addc_u32 s43, s43, 0
	v_lshl_add_u64 v[2:3], s[42:43], 0, v[202:203]
	global_load_dwordx4 v[208:211], v[0:1], off
	global_load_dwordx4 v[212:215], v[0:1], off offset:1024
	global_load_dwordx4 v[216:219], v[0:1], off offset:2048
	global_load_dwordx4 v[220:223], v[0:1], off offset:3072
	global_load_dwordx4 v[224:227], v[2:3], off
	global_load_dwordx4 v[228:231], v[2:3], off offset:1024
	global_load_dwordx4 v[232:235], v[2:3], off offset:2048
	global_load_dwordx4 v[236:239], v[2:3], off offset:3072
	s_lshr_b32 s39, s80, 1
	s_and_b32 s39, s39, 0x3800000
	s_lshr_b32 s47, s80, 3
	s_and_b32 s47, s47, 0x1fff80
	s_or_b32 s39, s39, s47
	s_add_u32 s46, s46, s39
	s_add_u32 s46, s58, s46
	s_addc_u32 s47, s59, 0
	v_lshl_add_u64 v[242:243], s[46:47], 0, v[204:205]
	v_mov_b32_e32 v10, s44
	s_waitcnt vmcnt(8)
	v_pk_mul_f32 v[142:143], v[142:143], v[8:9] op_sel_hi:[1,0]
	v_pk_mul_f32 v[150:151], v[150:151], v[8:9] op_sel_hi:[1,0]
	v_cvt_scalef32_pk_fp4_f32 v244, v142, v143, 1.0
	v_pk_mul_f32 v[144:145], v[144:145], v[8:9] op_sel_hi:[1,0]
	v_cvt_scalef32_pk_fp4_f32 v245, v150, v151, 1.0
	v_pk_mul_f32 v[152:153], v[152:153], v[8:9] op_sel_hi:[1,0]
	v_cvt_scalef32_pk_fp4_f32 v244, v144, v145, 1.0 op_sel:[0,0,1,0]
	v_pk_mul_f32 v[146:147], v[146:147], v[8:9] op_sel_hi:[1,0]
	v_cvt_scalef32_pk_fp4_f32 v245, v152, v153, 1.0 op_sel:[0,0,1,0]
	v_pk_mul_f32 v[154:155], v[154:155], v[8:9] op_sel_hi:[1,0]
	v_cvt_scalef32_pk_fp4_f32 v244, v146, v147, 1.0 op_sel:[0,0,0,1]
	v_pk_mul_f32 v[148:149], v[148:149], v[8:9] op_sel_hi:[1,0]
	v_cvt_scalef32_pk_fp4_f32 v245, v154, v155, 1.0 op_sel:[0,0,0,1]
	v_pk_mul_f32 v[156:157], v[156:157], v[8:9] op_sel_hi:[1,0]
	v_cvt_scalef32_pk_fp4_f32 v244, v148, v149, 1.0 op_sel:[0,0,1,1]
	v_pk_mul_f32 v[158:159], v[158:159], v[8:9] op_sel_hi:[1,0]
	v_cvt_scalef32_pk_fp4_f32 v245, v156, v157, 1.0 op_sel:[0,0,1,1]
	v_pk_mul_f32 v[166:167], v[166:167], v[8:9] op_sel_hi:[1,0]
	v_cvt_scalef32_pk_fp4_f32 v246, v158, v159, 1.0
	v_pk_mul_f32 v[160:161], v[160:161], v[8:9] op_sel_hi:[1,0]
	v_cvt_scalef32_pk_fp4_f32 v247, v166, v167, 1.0
	v_pk_mul_f32 v[168:169], v[168:169], v[8:9] op_sel_hi:[1,0]
	v_cvt_scalef32_pk_fp4_f32 v246, v160, v161, 1.0 op_sel:[0,0,1,0]
	v_pk_mul_f32 v[162:163], v[162:163], v[8:9] op_sel_hi:[1,0]
	v_cvt_scalef32_pk_fp4_f32 v247, v168, v169, 1.0 op_sel:[0,0,1,0]
	v_pk_mul_f32 v[170:171], v[170:171], v[8:9] op_sel_hi:[1,0]
	v_cvt_scalef32_pk_fp4_f32 v246, v162, v163, 1.0 op_sel:[0,0,0,1]
	v_pk_mul_f32 v[164:165], v[164:165], v[8:9] op_sel_hi:[1,0]
	v_cvt_scalef32_pk_fp4_f32 v247, v170, v171, 1.0 op_sel:[0,0,0,1]
	v_pk_mul_f32 v[172:173], v[172:173], v[8:9] op_sel_hi:[1,0]
	v_cvt_scalef32_pk_fp4_f32 v246, v164, v165, 1.0 op_sel:[0,0,1,1]
	v_cvt_scalef32_pk_fp4_f32 v247, v172, v173, 1.0 op_sel:[0,0,1,1]
	s_nop 0
	ds_write_b16 v200, v244
	ds_write_b16_d16_hi v200, v244 offset:128
	ds_write_b16 v200, v245 offset:256
	ds_write_b16_d16_hi v200, v245 offset:384
	ds_write_b16 v200, v246 offset:512
	ds_write_b16_d16_hi v200, v246 offset:640
	ds_write_b16 v200, v247 offset:768
	ds_write_b16_d16_hi v200, v247 offset:896
	ds_read_b128 v[248:251], v201
	s_waitcnt lgkmcnt(0)
	global_store_dwordx4 v[240:241], v[248:251], off
	s_add_i32 s38, s38, s99
	s_add_i32 s3, s3, s100
	s_cmp_lt_i32 s38, s98
	s_cbranch_scc0 .Lcv_lastB
	s_cmpk_gt_i32 s38, 0xfff
	s_cselect_b32 s42, s54, s52
	s_cselect_b32 s43, s55, s53
	s_mov_b32 s46, 0x2c00000
	s_cselect_b32 s46, 0xac00000, s46
	s_mov_b32 s44, 0x42800000
	s_cselect_b32 s44, 0x41500000, s44
	s_and_b32 s39, s3, 0x1ffe000
	s_or_b32 s80, s39, s2
	s_lshl_b32 s39, s80, 2
	s_add_u32 s42, s42, s39
	s_addc_u32 s43, s43, 0
	v_lshl_add_u64 v[0:1], s[42:43], 0, v[202:203]
	s_add_u32 s42, s42, 0x1000
	s_addc_u32 s43, s43, 0
	v_lshl_add_u64 v[2:3], s[42:43], 0, v[202:203]
	global_load_dwordx4 v[142:145], v[0:1], off
	global_load_dwordx4 v[146:149], v[0:1], off offset:1024
	global_load_dwordx4 v[150:153], v[0:1], off offset:2048
	global_load_dwordx4 v[154:157], v[0:1], off offset:3072
	global_load_dwordx4 v[158:161], v[2:3], off
	global_load_dwordx4 v[162:165], v[2:3], off offset:1024
	global_load_dwordx4 v[166:169], v[2:3], off offset:2048
	global_load_dwordx4 v[170:173], v[2:3], off offset:3072
	s_lshr_b32 s39, s80, 1
	s_and_b32 s39, s39, 0x3800000
	s_lshr_b32 s47, s80, 3
	s_and_b32 s47, s47, 0x1fff80
	s_or_b32 s39, s39, s47
	s_add_u32 s46, s46, s39
	s_add_u32 s46, s58, s46
	s_addc_u32 s47, s59, 0
	v_lshl_add_u64 v[240:241], s[46:47], 0, v[204:205]
	v_mov_b32_e32 v8, s44
	s_waitcnt vmcnt(8)
	v_pk_mul_f32 v[208:209], v[208:209], v[10:11] op_sel_hi:[1,0]
	v_pk_mul_f32 v[216:217], v[216:217], v[10:11] op_sel_hi:[1,0]
	v_cvt_scalef32_pk_fp4_f32 v244, v208, v209, 1.0
	v_pk_mul_f32 v[210:211], v[210:211], v[10:11] op_sel_hi:[1,0]
	v_cvt_scalef32_pk_fp4_f32 v245, v216, v217, 1.0
	v_pk_mul_f32 v[218:219], v[218:219], v[10:11] op_sel_hi:[1,0]
	v_cvt_scalef32_pk_fp4_f32 v244, v210, v211, 1.0 op_sel:[0,0,1,0]
	v_pk_mul_f32 v[212:213], v[212:213], v[10:11] op_sel_hi:[1,0]
	v_cvt_scalef32_pk_fp4_f32 v245, v218, v219, 1.0 op_sel:[0,0,1,0]
	v_pk_mul_f32 v[220:221], v[220:221], v[10:11] op_sel_hi:[1,0]
	v_cvt_scalef32_pk_fp4_f32 v244, v212, v213, 1.0 op_sel:[0,0,0,1]
	v_pk_mul_f32 v[214:215], v[214:215], v[10:11] op_sel_hi:[1,0]
	v_cvt_scalef32_pk_fp4_f32 v245, v220, v221, 1.0 op_sel:[0,0,0,1]
	v_pk_mul_f32 v[222:223], v[222:223], v[10:11] op_sel_hi:[1,0]
	v_cvt_scalef32_pk_fp4_f32 v244, v214, v215, 1.0 op_sel:[0,0,1,1]
	v_pk_mul_f32 v[224:225], v[224:225], v[10:11] op_sel_hi:[1,0]
	v_cvt_scalef32_pk_fp4_f32 v245, v222, v223, 1.0 op_sel:[0,0,1,1]
	v_pk_mul_f32 v[232:233], v[232:233], v[10:11] op_sel_hi:[1,0]
	v_cvt_scalef32_pk_fp4_f32 v246, v224, v225, 1.0
	v_pk_mul_f32 v[226:227], v[226:227], v[10:11] op_sel_hi:[1,0]
	v_cvt_scalef32_pk_fp4_f32 v247, v232, v233, 1.0
	v_pk_mul_f32 v[234:235], v[234:235], v[10:11] op_sel_hi:[1,0]
	v_cvt_scalef32_pk_fp4_f32 v246, v226, v227, 1.0 op_sel:[0,0,1,0]
	v_pk_mul_f32 v[228:229], v[228:229], v[10:11] op_sel_hi:[1,0]
	v_cvt_scalef32_pk_fp4_f32 v247, v234, v235, 1.0 op_sel:[0,0,1,0]
	v_pk_mul_f32 v[236:237], v[236:237], v[10:11] op_sel_hi:[1,0]
	v_cvt_scalef32_pk_fp4_f32 v246, v228, v229, 1.0 op_sel:[0,0,0,1]
	v_pk_mul_f32 v[230:231], v[230:231], v[10:11] op_sel_hi:[1,0]
	v_cvt_scalef32_pk_fp4_f32 v247, v236, v237, 1.0 op_sel:[0,0,0,1]
	v_pk_mul_f32 v[238:239], v[238:239], v[10:11] op_sel_hi:[1,0]
	v_cvt_scalef32_pk_fp4_f32 v246, v230, v231, 1.0 op_sel:[0,0,1,1]
	v_cvt_scalef32_pk_fp4_f32 v247, v238, v239, 1.0 op_sel:[0,0,1,1]
	s_nop 0
	ds_write_b16 v200, v244
	ds_write_b16_d16_hi v200, v244 offset:128
	ds_write_b16 v200, v245 offset:256
	ds_write_b16_d16_hi v200, v245 offset:384
	ds_write_b16 v200, v246 offset:512
	ds_write_b16_d16_hi v200, v246 offset:640
	ds_write_b16 v200, v247 offset:768
	ds_write_b16_d16_hi v200, v247 offset:896
	ds_read_b128 v[248:251], v201
	s_waitcnt lgkmcnt(0)
	global_store_dwordx4 v[242:243], v[248:251], off
	s_branch .Lcv_loop
.Lcv_lastA:
	s_waitcnt vmcnt(0)
	v_pk_mul_f32 v[142:143], v[142:143], v[8:9] op_sel_hi:[1,0]
	v_pk_mul_f32 v[150:151], v[150:151], v[8:9] op_sel_hi:[1,0]
	v_cvt_scalef32_pk_fp4_f32 v244, v142, v143, 1.0
	v_pk_mul_f32 v[144:145], v[144:145], v[8:9] op_sel_hi:[1,0]
	v_cvt_scalef32_pk_fp4_f32 v245, v150, v151, 1.0
	v_pk_mul_f32 v[152:153], v[152:153], v[8:9] op_sel_hi:[1,0]
	v_cvt_scalef32_pk_fp4_f32 v244, v144, v145, 1.0 op_sel:[0,0,1,0]
	v_pk_mul_f32 v[146:147], v[146:147], v[8:9] op_sel_hi:[1,0]
	v_cvt_scalef32_pk_fp4_f32 v245, v152, v153, 1.0 op_sel:[0,0,1,0]
	v_pk_mul_f32 v[154:155], v[154:155], v[8:9] op_sel_hi:[1,0]
	v_cvt_scalef32_pk_fp4_f32 v244, v146, v147, 1.0 op_sel:[0,0,0,1]
	v_pk_mul_f32 v[148:149], v[148:149], v[8:9] op_sel_hi:[1,0]
	v_cvt_scalef32_pk_fp4_f32 v245, v154, v155, 1.0 op_sel:[0,0,0,1]
	v_pk_mul_f32 v[156:157], v[156:157], v[8:9] op_sel_hi:[1,0]
	v_cvt_scalef32_pk_fp4_f32 v244, v148, v149, 1.0 op_sel:[0,0,1,1]
	v_pk_mul_f32 v[158:159], v[158:159], v[8:9] op_sel_hi:[1,0]
	v_cvt_scalef32_pk_fp4_f32 v245, v156, v157, 1.0 op_sel:[0,0,1,1]
	v_pk_mul_f32 v[166:167], v[166:167], v[8:9] op_sel_hi:[1,0]
	v_cvt_scalef32_pk_fp4_f32 v246, v158, v159, 1.0
	v_pk_mul_f32 v[160:161], v[160:161], v[8:9] op_sel_hi:[1,0]
	v_cvt_scalef32_pk_fp4_f32 v247, v166, v167, 1.0
	v_pk_mul_f32 v[168:169], v[168:169], v[8:9] op_sel_hi:[1,0]
	v_cvt_scalef32_pk_fp4_f32 v246, v160, v161, 1.0 op_sel:[0,0,1,0]
	v_pk_mul_f32 v[162:163], v[162:163], v[8:9] op_sel_hi:[1,0]
	v_cvt_scalef32_pk_fp4_f32 v247, v168, v169, 1.0 op_sel:[0,0,1,0]
	v_pk_mul_f32 v[170:171], v[170:171], v[8:9] op_sel_hi:[1,0]
	v_cvt_scalef32_pk_fp4_f32 v246, v162, v163, 1.0 op_sel:[0,0,0,1]
	v_pk_mul_f32 v[164:165], v[164:165], v[8:9] op_sel_hi:[1,0]
	v_cvt_scalef32_pk_fp4_f32 v247, v170, v171, 1.0 op_sel:[0,0,0,1]
	v_pk_mul_f32 v[172:173], v[172:173], v[8:9] op_sel_hi:[1,0]
	v_cvt_scalef32_pk_fp4_f32 v246, v164, v165, 1.0 op_sel:[0,0,1,1]
	v_cvt_scalef32_pk_fp4_f32 v247, v172, v173, 1.0 op_sel:[0,0,1,1]
	s_nop 0
	ds_write_b16 v200, v244
	ds_write_b16_d16_hi v200, v244 offset:128
	ds_write_b16 v200, v245 offset:256
	ds_write_b16_d16_hi v200, v245 offset:384
	ds_write_b16 v200, v246 offset:512
	ds_write_b16_d16_hi v200, v246 offset:640
	ds_write_b16 v200, v247 offset:768
	ds_write_b16_d16_hi v200, v247 offset:896
	ds_read_b128 v[248:251], v201
	s_waitcnt lgkmcnt(0)
	global_store_dwordx4 v[240:241], v[248:251], off
	s_branch .LBB0_641
.Lcv_lastB:
	s_waitcnt vmcnt(0)
	v_pk_mul_f32 v[208:209], v[208:209], v[10:11] op_sel_hi:[1,0]
	v_pk_mul_f32 v[216:217], v[216:217], v[10:11] op_sel_hi:[1,0]
	v_cvt_scalef32_pk_fp4_f32 v244, v208, v209, 1.0
	v_pk_mul_f32 v[210:211], v[210:211], v[10:11] op_sel_hi:[1,0]
	v_cvt_scalef32_pk_fp4_f32 v245, v216, v217, 1.0
	v_pk_mul_f32 v[218:219], v[218:219], v[10:11] op_sel_hi:[1,0]
	v_cvt_scalef32_pk_fp4_f32 v244, v210, v211, 1.0 op_sel:[0,0,1,0]
	v_pk_mul_f32 v[212:213], v[212:213], v[10:11] op_sel_hi:[1,0]
	v_cvt_scalef32_pk_fp4_f32 v245, v218, v219, 1.0 op_sel:[0,0,1,0]
	v_pk_mul_f32 v[220:221], v[220:221], v[10:11] op_sel_hi:[1,0]
	v_cvt_scalef32_pk_fp4_f32 v244, v212, v213, 1.0 op_sel:[0,0,0,1]
	v_pk_mul_f32 v[214:215], v[214:215], v[10:11] op_sel_hi:[1,0]
	v_cvt_scalef32_pk_fp4_f32 v245, v220, v221, 1.0 op_sel:[0,0,0,1]
	v_pk_mul_f32 v[222:223], v[222:223], v[10:11] op_sel_hi:[1,0]
	v_cvt_scalef32_pk_fp4_f32 v244, v214, v215, 1.0 op_sel:[0,0,1,1]
	v_pk_mul_f32 v[224:225], v[224:225], v[10:11] op_sel_hi:[1,0]
	v_cvt_scalef32_pk_fp4_f32 v245, v222, v223, 1.0 op_sel:[0,0,1,1]
	v_pk_mul_f32 v[232:233], v[232:233], v[10:11] op_sel_hi:[1,0]
	v_cvt_scalef32_pk_fp4_f32 v246, v224, v225, 1.0
	v_pk_mul_f32 v[226:227], v[226:227], v[10:11] op_sel_hi:[1,0]
	v_cvt_scalef32_pk_fp4_f32 v247, v232, v233, 1.0
	v_pk_mul_f32 v[234:235], v[234:235], v[10:11] op_sel_hi:[1,0]
	v_cvt_scalef32_pk_fp4_f32 v246, v226, v227, 1.0 op_sel:[0,0,1,0]
	v_pk_mul_f32 v[228:229], v[228:229], v[10:11] op_sel_hi:[1,0]
	v_cvt_scalef32_pk_fp4_f32 v247, v234, v235, 1.0 op_sel:[0,0,1,0]
	v_pk_mul_f32 v[236:237], v[236:237], v[10:11] op_sel_hi:[1,0]
	v_cvt_scalef32_pk_fp4_f32 v246, v228, v229, 1.0 op_sel:[0,0,0,1]
	v_pk_mul_f32 v[230:231], v[230:231], v[10:11] op_sel_hi:[1,0]
	v_cvt_scalef32_pk_fp4_f32 v247, v236, v237, 1.0 op_sel:[0,0,0,1]
	v_pk_mul_f32 v[238:239], v[238:239], v[10:11] op_sel_hi:[1,0]
	v_cvt_scalef32_pk_fp4_f32 v246, v230, v231, 1.0 op_sel:[0,0,1,1]
	v_cvt_scalef32_pk_fp4_f32 v247, v238, v239, 1.0 op_sel:[0,0,1,1]
	s_nop 0
	ds_write_b16 v200, v244
	ds_write_b16_d16_hi v200, v244 offset:128
	ds_write_b16 v200, v245 offset:256
	ds_write_b16_d16_hi v200, v245 offset:384
	ds_write_b16 v200, v246 offset:512
	ds_write_b16_d16_hi v200, v246 offset:640
	ds_write_b16 v200, v247 offset:768
	ds_write_b16_d16_hi v200, v247 offset:896
	ds_read_b128 v[248:251], v201
	s_waitcnt lgkmcnt(0)
	global_store_dwordx4 v[242:243], v[248:251], off

	.amdhsa_kernel _Z10fwd_kernel6Params
		.amdhsa_group_segment_fixed_size 73744
		.amdhsa_private_segment_fixed_size 0
		.amdhsa_kernarg_size 520
		.amdhsa_user_sgpr_count 2
		.amdhsa_user_sgpr_dispatch_ptr 0
		.amdhsa_user_sgpr_queue_ptr 0
		.amdhsa_user_sgpr_kernarg_segment_ptr 1
		.amdhsa_user_sgpr_dispatch_id 0
		.amdhsa_user_sgpr_kernarg_preload_length 0
		.amdhsa_user_sgpr_kernarg_preload_offset 0
		.amdhsa_user_sgpr_private_segment_size 0
		.amdhsa_uses_dynamic_stack 0
		.amdhsa_enable_private_segment 0
		.amdhsa_system_sgpr_workgroup_id_x 1
		.amdhsa_system_sgpr_workgroup_id_y 0
		.amdhsa_system_sgpr_workgroup_id_z 0
		.amdhsa_system_sgpr_workgroup_info 0
		.amdhsa_system_vgpr_workitem_id 2
		.amdhsa_next_free_vgpr 256
		.amdhsa_next_free_sgpr 102
		.amdhsa_accum_offset 256
		.amdhsa_reserve_vcc 1
		.amdhsa_float_round_mode_32 0
		.amdhsa_float_round_mode_16_64 0
		.amdhsa_float_denorm_mode_32 3
		.amdhsa_float_denorm_mode_16_64 3
		.amdhsa_dx10_clamp 1
		.amdhsa_ieee_mode 1
		.amdhsa_fp16_overflow 0
		.amdhsa_tg_split 0
		.amdhsa_exception_fp_ieee_invalid_op 0
		.amdhsa_exception_fp_denorm_src 0
		.amdhsa_exception_fp_ieee_div_zero 0
		.amdhsa_exception_fp_ieee_overflow 0
		.amdhsa_exception_fp_ieee_underflow 0
		.amdhsa_exception_fp_ieee_inexact 0
		.amdhsa_exception_int_div_zero 0
	.end_amdhsa_kernel

amdhsa.kernels:
  - .agpr_count:     0
    .args:
      - .offset:         0
        .size:           264
        .value_kind:     by_value
      - .offset:         264
        .size:           4
        .value_kind:     hidden_block_count_x
      - .offset:         268
        .size:           4
        .value_kind:     hidden_block_count_y
      - .offset:         272
        .size:           4
        .value_kind:     hidden_block_count_z
      - .offset:         276
        .size:           2
        .value_kind:     hidden_group_size_x
      - .offset:         278
        .size:           2
        .value_kind:     hidden_group_size_y
      - .offset:         280
        .size:           2
        .value_kind:     hidden_group_size_z
      - .offset:         282
        .size:           2
        .value_kind:     hidden_remainder_x
      - .offset:         284
        .size:           2
        .value_kind:     hidden_remainder_y
      - .offset:         286
        .size:           2
        .value_kind:     hidden_remainder_z
      - .offset:         304
        .size:           8
        .value_kind:     hidden_global_offset_x
      - .offset:         312
        .size:           8
        .value_kind:     hidden_global_offset_y
      - .offset:         320
        .size:           8
        .value_kind:     hidden_global_offset_z
      - .offset:         328
        .size:           2
        .value_kind:     hidden_grid_dims
      - .offset:         352
        .size:           8
        .value_kind:     hidden_multigrid_sync_arg
    .group_segment_fixed_size: 73744
    .kernarg_segment_align: 8
    .kernarg_segment_size: 520
    .language:       OpenCL C
    .language_version:
      - 2
      - 0
    .max_flat_workgroup_size: 256
    .name:           _Z10fwd_kernel6Params
    .private_segment_fixed_size: 0
    .sgpr_count:     108
    .sgpr_spill_count: 146
    .symbol:         _Z10fwd_kernel6Params.kd
    .uniform_work_group_size: 1
    .uses_dynamic_stack: false
    .vgpr_count:     256
    .vgpr_spill_count: 0
    .wavefront_size: 64
